# sample-row GEMM units of phases 1, 8, 12, 17: all 32 operand loads issued up front into fresh registers (the compiler recycled two B registers, every MFMA waited for a just-issued load)
# baseline (speedup 1.0000x reference)
; #define MFMA32(a, b, c) __builtin_amdgcn_mfma_f32_32x32x16_bf16((a), (b), (c), 0, 0, 0)
; DI bfr f2bf(float a) { return (bfr)(pack2(a, 0.f) & 0xffffu); }
; DI int crow(int reg, int h) { return (reg & 3) + 8 * (reg >> 2) + 4 * h; }
; template <bool RS, class Epi, class RowF>
; DI void gemm_sample(const bfr* __restrict__ A, int lda, const bfr* __restrict__ Bt, int ldb, int K, int N, char* smem, Epi epi, RowF rowf) {
;     ...
;     if (K == 1024) {
; #pragma unroll
;       for (int ks = 0; ks < 16; ++ks) {
;         bf16x8 af = *(const bf16x8*)(ap + ks * 16);
;         bf16x8 bf = *(const bf16x8*)(bp + (size_t)(ks >> 1) * ldb * 32 + (ks & 1) * 16);
;         acc = MFMA32(af, bf, acc);
;       }
;     } else {
;       for (int ks = 0; ks < (kq >> 4); ++ks) {
;         bf16x8 af = *(const bf16x8*)(ap + ks * 16);
;         bf16x8 bf = *(const bf16x8*)(bp + (size_t)(ks >> 1) * ldb * 32 + (ks & 1) * 16);
;         acc = MFMA32(af, bf, acc);
;       }
;     }
; #pragma unroll
;     for (int q = 0; q < 16; ++q) red[(wid * 16 + q) * 64 + lane] = acc[q];
;     __syncthreads();
; #pragma unroll
;     for (int e = 0; e < 4; ++e) {
;       const int q = wid + e * 4;
;       const float v = red[q * 64 + lane] + red[(16 + q) * 64 + lane] + red[(32 + q) * 64 + lane] + red[(48 + q) * 64 + lane];
;       const int row = NPR + mu * 32 + crow(q, hl), col = nu * 32 + r;
;       float x = epi(row, col, v);
;       if (RS) {
;         float s2 = half32_sum_hi(x * x);
;         if (r == 31) rowf(row, s2);
;       }
;     }
; DI void phase_gemm_in_even(const Params& p, char* smem) {
;     ...
;                        [=](int row, int col, float v) -> float { PB[(size_t)row * EINP + col] = f2bf(v); return 0.f; },
.LBB0_115:
	s_and_b32 s16, s4, 0x60
	s_and_b32 s0, s2, 0xffffffe0
	s_bitset1_b32 s16, 14
	s_ashr_i32 s1, s0, 31
	v_or_b32_e32 v2, s16, v24
	v_lshl_add_u64 v[0:1], s[0:1], 0, v[20:21]
	v_lshlrev_b32_e32 v16, 11, v2
	v_lshlrev_b64 v[0:1], 6, v[0:1]
	v_lshl_add_u64 v[8:9], v[18:19], 0, v[16:17]
	v_lshl_add_u64 v[10:11], v[22:23], 0, v[0:1]
	global_load_dwordx4 v[0:3], v[8:9], off
	global_load_dwordx4 v[4:7], v[10:11], off
	global_load_dwordx4 v[36:39], v[8:9], off offset:32
	global_load_dwordx4 v[40:43], v[10:11], off offset:32
	v_add_co_u32_e32 v104, vcc, s8, v10
	global_load_dwordx4 v[44:47], v[8:9], off offset:64
	global_load_dwordx4 v[48:51], v[8:9], off offset:96
	v_addc_co_u32_e32 v105, vcc, 0, v11, vcc
	global_load_dwordx4 v[52:55], v[8:9], off offset:128
	global_load_dwordx4 v[56:59], v[8:9], off offset:160
	global_load_dwordx4 v[60:63], v[8:9], off offset:192
	global_load_dwordx4 v[64:67], v[8:9], off offset:224
	global_load_dwordx4 v[68:71], v[8:9], off offset:256
	global_load_dwordx4 v[72:75], v[8:9], off offset:288
	global_load_dwordx4 v[76:79], v[8:9], off offset:320
	global_load_dwordx4 v[80:83], v[8:9], off offset:352
	global_load_dwordx4 v[84:87], v[8:9], off offset:384
	global_load_dwordx4 v[88:91], v[8:9], off offset:416
	global_load_dwordx4 v[92:95], v[8:9], off offset:448
	global_load_dwordx4 v[96:99], v[8:9], off offset:480
	global_load_dwordx4 v[100:103], v[104:105], off
	v_add_co_u32_e32 v108, vcc, s9, v10
	global_load_dwordx4 v[104:107], v[104:105], off offset:32
	s_nop 0
	v_addc_co_u32_e32 v109, vcc, 0, v11, vcc
	v_add_co_u32_e32 v110, vcc, s10, v10
	v_or_b32_e32 v16, s16, v25
	s_nop 0
	v_addc_co_u32_e32 v111, vcc, 0, v11, vcc
	v_add_co_u32_e32 v112, vcc, s11, v10
	v_or_b32_e32 v35, v16, v27
	s_nop 0
	v_addc_co_u32_e32 v113, vcc, 0, v11, vcc
	v_add_co_u32_e32 v114, vcc, s12, v10
	s_add_i32 s15, s15, s34
	s_nop 0
	v_addc_co_u32_e32 v115, vcc, 0, v11, vcc
	v_add_co_u32_e32 v116, vcc, s13, v10
	s_add_i32 s2, s2, s3
	s_nop 0
	v_addc_co_u32_e32 v117, vcc, 0, v11, vcc
	v_add_co_u32_e32 v118, vcc, s14, v10
	s_add_i32 s4, s4, s5
	s_nop 0
	v_addc_co_u32_e32 v119, vcc, 0, v11, vcc
	s_cmpk_lt_i32 s15, 0x1c0
	global_load_dwordx4 v[120:123], v[108:109], off
	global_load_dwordx4 v[124:127], v[108:109], off offset:32
	global_load_dwordx4 v[128:131], v[110:111], off
	global_load_dwordx4 v[132:135], v[110:111], off offset:32
	global_load_dwordx4 v[136:139], v[112:113], off
	global_load_dwordx4 v[140:143], v[112:113], off offset:32
	global_load_dwordx4 v[144:147], v[114:115], off
	global_load_dwordx4 v[148:151], v[114:115], off offset:32
	global_load_dwordx4 v[152:155], v[116:117], off
	global_load_dwordx4 v[156:159], v[116:117], off offset:32
	global_load_dwordx4 v[160:163], v[118:119], off
	global_load_dwordx4 v[164:167], v[118:119], off offset:32
	s_waitcnt vmcnt(30)
	v_mfma_f32_32x32x16_bf16 v[0:15], v[0:3], v[4:7], 0
	s_waitcnt vmcnt(28)
	v_mfma_f32_32x32x16_bf16 v[0:15], v[36:39], v[40:43], v[0:15]
	s_waitcnt vmcnt(13)
	v_mfma_f32_32x32x16_bf16 v[0:15], v[44:47], v[100:103], v[0:15]
	s_waitcnt vmcnt(12)
	v_mfma_f32_32x32x16_bf16 v[0:15], v[48:51], v[104:107], v[0:15]
	v_or_b32_e32 v48, s0, v24
	v_ashrrev_i32_e32 v49, 31, v48
	v_add_u32_e32 v50, v33, v16
	s_waitcnt vmcnt(11)
	v_mfma_f32_32x32x16_bf16 v[0:15], v[52:55], v[120:123], v[0:15]
	s_waitcnt vmcnt(10)
	v_mfma_f32_32x32x16_bf16 v[0:15], v[56:59], v[124:127], v[0:15]
	s_waitcnt vmcnt(9)
	v_mfma_f32_32x32x16_bf16 v[0:15], v[60:63], v[128:131], v[0:15]
	s_waitcnt vmcnt(8)
	v_mfma_f32_32x32x16_bf16 v[0:15], v[64:67], v[132:135], v[0:15]
	s_waitcnt vmcnt(7)
	v_mfma_f32_32x32x16_bf16 v[0:15], v[68:71], v[136:139], v[0:15]
	s_waitcnt vmcnt(6)
	v_mfma_f32_32x32x16_bf16 v[0:15], v[72:75], v[140:143], v[0:15]
	s_waitcnt vmcnt(5)
	v_mfma_f32_32x32x16_bf16 v[0:15], v[76:79], v[144:147], v[0:15]
	s_waitcnt vmcnt(4)
	v_mfma_f32_32x32x16_bf16 v[0:15], v[80:83], v[148:151], v[0:15]
	s_waitcnt vmcnt(3)
	v_mfma_f32_32x32x16_bf16 v[0:15], v[84:87], v[152:155], v[0:15]
	s_waitcnt vmcnt(2)
	v_mfma_f32_32x32x16_bf16 v[0:15], v[88:91], v[156:159], v[0:15]
	v_lshl_add_u64 v[36:37], v[48:49], 1, s[6:7]
	v_add_u32_e32 v48, v29, v16
	v_add_u32_e32 v49, v31, v16
	v_mul_u32_u24_e32 v16, 0x1c00, v35
	v_lshl_add_u64 v[38:39], v[36:37], 0, v[16:17]
	v_mul_u32_u24_e32 v16, 0x1c00, v48
	s_waitcnt vmcnt(1)
	v_mfma_f32_32x32x16_bf16 v[0:15], v[92:95], v[160:163], v[0:15]
	v_lshl_add_u64 v[40:41], v[36:37], 0, v[16:17]
	v_mul_u32_u24_e32 v16, 0x1c00, v49
	v_lshl_add_u64 v[42:43], v[36:37], 0, v[16:17]
	v_mul_u32_u24_e32 v16, 0x1c00, v50
	v_lshl_add_u64 v[36:37], v[36:37], 0, v[16:17]
	s_waitcnt vmcnt(0)
	v_mfma_f32_32x32x16_bf16 v[0:15], v[96:99], v[164:167], v[0:15]
	s_nop 11
	ds_write2st64_b32 v34, v0, v1 offset1:1
	ds_write2st64_b32 v34, v2, v3 offset0:2 offset1:3
	ds_write2st64_b32 v34, v4, v5 offset0:4 offset1:5
	ds_write2st64_b32 v34, v6, v7 offset0:6 offset1:7
	ds_write2st64_b32 v34, v8, v9 offset0:8 offset1:9
	ds_write2st64_b32 v34, v10, v11 offset0:10 offset1:11
	ds_write2st64_b32 v34, v12, v13 offset0:12 offset1:13
	ds_write2st64_b32 v34, v14, v15 offset0:14 offset1:15
	s_waitcnt lgkmcnt(0)
	s_barrier
	ds_read2st64_b32 v[0:1], v26 offset1:16
	ds_read2st64_b32 v[2:3], v26 offset0:32 offset1:48
	ds_read2st64_b32 v[4:5], v28 offset1:16
	ds_read2st64_b32 v[6:7], v28 offset0:32 offset1:48
	ds_read2st64_b32 v[8:9], v30 offset1:16
	ds_read2st64_b32 v[10:11], v30 offset0:32 offset1:48
	ds_read2st64_b32 v[12:13], v32 offset1:16
	ds_read2st64_b32 v[14:15], v32 offset0:32 offset1:48
	s_waitcnt lgkmcnt(7)
	v_add_f32_e32 v0, v0, v1
	s_waitcnt lgkmcnt(5)
	v_add_f32_e32 v1, v4, v5
	s_waitcnt lgkmcnt(3)
	v_add_f32_e32 v4, v8, v9
	s_waitcnt lgkmcnt(1)
	v_add_f32_e32 v5, v12, v13
	v_add_f32_e32 v0, v0, v2
	v_add_f32_e32 v1, v1, v6
	v_add_f32_e32 v2, v4, v10
	s_waitcnt lgkmcnt(0)
	v_add_f32_e32 v4, v5, v14
	v_add_f32_e32 v0, v0, v3
	v_add_f32_e32 v1, v1, v7
	v_add_f32_e32 v2, v2, v11
	v_add_f32_e32 v3, v4, v15
	v_cvt_pk_bf16_f32 v0, v0, s0
	v_cvt_pk_bf16_f32 v1, v1, s0
	v_cvt_pk_bf16_f32 v2, v2, s0
	v_cvt_pk_bf16_f32 v3, v3, s0
	global_store_short v[38:39], v0, off
	global_store_short v[40:41], v1, off
	global_store_short v[42:43], v2, off
	global_store_short v[36:37], v3, off
	s_barrier
	s_cbranch_scc1 .LBB0_115

; #define MFMA32(a, b, c) __builtin_amdgcn_mfma_f32_32x32x16_bf16((a), (b), (c), 0, 0, 0)
; DI int crow(int reg, int h) { return (reg & 3) + 8 * (reg >> 2) + 4 * h; }
; template <bool RS, class Epi, class RowF>
; DI void gemm_sample(const bfr* __restrict__ A, int lda, const bfr* __restrict__ Bt, int ldb, int K, int N, char* smem, Epi epi, RowF rowf) {
;     ...
;     if (K == 1024) {
; #pragma unroll
;       for (int ks = 0; ks < 16; ++ks) {
;         bf16x8 af = *(const bf16x8*)(ap + ks * 16);
;         bf16x8 bf = *(const bf16x8*)(bp + (size_t)(ks >> 1) * ldb * 32 + (ks & 1) * 16);
;         acc = MFMA32(af, bf, acc);
;       }
;     } else {
;       for (int ks = 0; ks < (kq >> 4); ++ks) {
;         bf16x8 af = *(const bf16x8*)(ap + ks * 16);
;         bf16x8 bf = *(const bf16x8*)(bp + (size_t)(ks >> 1) * ldb * 32 + (ks & 1) * 16);
;         acc = MFMA32(af, bf, acc);
;       }
;     }
; #pragma unroll
;     for (int q = 0; q < 16; ++q) red[(wid * 16 + q) * 64 + lane] = acc[q];
;     __syncthreads();
; #pragma unroll
;     for (int e = 0; e < 4; ++e) {
;       const int q = wid + e * 4;
;       const float v = red[q * 64 + lane] + red[(16 + q) * 64 + lane] + red[(32 + q) * 64 + lane] + red[(48 + q) * 64 + lane];
;       const int row = NPR + mu * 32 + crow(q, hl), col = nu * 32 + r;
.LBB0_919:
	s_and_b32 s1, s16, 0x60
	s_and_b32 s0, s14, 0xffffffe0
	s_or_b32 s4, s1, 0x4000
	s_ashr_i32 s1, s0, 31
	v_or_b32_e32 v2, s4, v24
	v_lshl_add_u64 v[0:1], s[0:1], 0, v[20:21]
	v_lshlrev_b32_e32 v16, 11, v2
	v_lshlrev_b64 v[0:1], 6, v[0:1]
	v_lshl_add_u64 v[8:9], v[18:19], 0, v[16:17]
	v_lshl_add_u64 v[10:11], v[22:23], 0, v[0:1]
	global_load_dwordx4 v[0:3], v[8:9], off
	global_load_dwordx4 v[4:7], v[10:11], off
	global_load_dwordx4 v[36:39], v[8:9], off offset:32
	global_load_dwordx4 v[40:43], v[10:11], off offset:32
	v_add_co_u32_e32 v104, vcc, s18, v10
	global_load_dwordx4 v[44:47], v[8:9], off offset:64
	global_load_dwordx4 v[48:51], v[8:9], off offset:96
	v_addc_co_u32_e32 v105, vcc, 0, v11, vcc
	v_add_co_u32_e32 v106, vcc, s19, v10
	global_load_dwordx4 v[52:55], v[8:9], off offset:128
	global_load_dwordx4 v[56:59], v[8:9], off offset:160
	v_addc_co_u32_e32 v107, vcc, 0, v11, vcc
	v_add_co_u32_e32 v108, vcc, s20, v10
	global_load_dwordx4 v[60:63], v[8:9], off offset:192
	global_load_dwordx4 v[64:67], v[8:9], off offset:224
	v_addc_co_u32_e32 v109, vcc, 0, v11, vcc
	v_add_co_u32_e32 v110, vcc, s21, v10
	global_load_dwordx4 v[68:71], v[8:9], off offset:256
	global_load_dwordx4 v[72:75], v[8:9], off offset:288
	v_addc_co_u32_e32 v111, vcc, 0, v11, vcc
	v_add_co_u32_e32 v112, vcc, s22, v10
	global_load_dwordx4 v[76:79], v[8:9], off offset:320
	global_load_dwordx4 v[80:83], v[8:9], off offset:352
	v_addc_co_u32_e32 v113, vcc, 0, v11, vcc
	v_add_co_u32_e32 v114, vcc, s23, v10
	global_load_dwordx4 v[84:87], v[8:9], off offset:384
	global_load_dwordx4 v[88:91], v[8:9], off offset:416
	v_addc_co_u32_e32 v115, vcc, 0, v11, vcc
	v_add_co_u32_e32 v116, vcc, s24, v10
	global_load_dwordx4 v[92:95], v[8:9], off offset:448
	global_load_dwordx4 v[96:99], v[8:9], off offset:480
	v_addc_co_u32_e32 v117, vcc, 0, v11, vcc
	global_load_dwordx4 v[100:103], v[104:105], off
	v_or_b32_e32 v16, s4, v25
	s_add_i32 s26, s26, s34
	s_add_i32 s14, s14, s15
	s_add_i32 s16, s16, s17
	s_cmpk_lt_i32 s26, 0x80
	global_load_dwordx4 v[120:123], v[104:105], off offset:32
	global_load_dwordx4 v[124:127], v[106:107], off
	global_load_dwordx4 v[128:131], v[106:107], off offset:32
	global_load_dwordx4 v[132:135], v[108:109], off
	global_load_dwordx4 v[136:139], v[108:109], off offset:32
	global_load_dwordx4 v[140:143], v[110:111], off
	global_load_dwordx4 v[144:147], v[110:111], off offset:32
	global_load_dwordx4 v[148:151], v[112:113], off
	global_load_dwordx4 v[152:155], v[112:113], off offset:32
	global_load_dwordx4 v[156:159], v[114:115], off
	global_load_dwordx4 v[160:163], v[114:115], off offset:32
	global_load_dwordx4 v[164:167], v[116:117], off
	global_load_dwordx4 v[168:171], v[116:117], off offset:32
	s_waitcnt vmcnt(30)
	v_mfma_f32_32x32x16_bf16 v[0:15], v[0:3], v[4:7], 0
	s_waitcnt vmcnt(28)
	v_mfma_f32_32x32x16_bf16 v[0:15], v[36:39], v[40:43], v[0:15]
	s_waitcnt vmcnt(13)
	v_mfma_f32_32x32x16_bf16 v[0:15], v[44:47], v[100:103], v[0:15]
	v_or_b32_e32 v44, v27, v16
	s_waitcnt vmcnt(12)
	v_mfma_f32_32x32x16_bf16 v[0:15], v[48:51], v[120:123], v[0:15]
	s_waitcnt vmcnt(11)
	v_mfma_f32_32x32x16_bf16 v[0:15], v[52:55], v[124:127], v[0:15]
	s_waitcnt vmcnt(10)
	v_mfma_f32_32x32x16_bf16 v[0:15], v[56:59], v[128:131], v[0:15]
	s_waitcnt vmcnt(9)
	v_mfma_f32_32x32x16_bf16 v[0:15], v[60:63], v[132:135], v[0:15]
	s_waitcnt vmcnt(8)
	v_mfma_f32_32x32x16_bf16 v[0:15], v[64:67], v[136:139], v[0:15]
	s_waitcnt vmcnt(7)
	v_mfma_f32_32x32x16_bf16 v[0:15], v[68:71], v[140:143], v[0:15]
	s_waitcnt vmcnt(6)
	v_mfma_f32_32x32x16_bf16 v[0:15], v[72:75], v[144:147], v[0:15]
	s_waitcnt vmcnt(5)
	v_mfma_f32_32x32x16_bf16 v[0:15], v[76:79], v[148:151], v[0:15]
	s_waitcnt vmcnt(4)
	v_mfma_f32_32x32x16_bf16 v[0:15], v[80:83], v[152:155], v[0:15]
	s_waitcnt vmcnt(3)
	v_mfma_f32_32x32x16_bf16 v[0:15], v[84:87], v[156:159], v[0:15]
	s_waitcnt vmcnt(2)
	v_mfma_f32_32x32x16_bf16 v[0:15], v[88:91], v[160:163], v[0:15]
	s_waitcnt vmcnt(1)
	v_mfma_f32_32x32x16_bf16 v[0:15], v[92:95], v[164:167], v[0:15]
	v_add_u32_e32 v40, v16, v29
	v_add_u32_e32 v41, v16, v31
	v_add_u32_e32 v42, v16, v33
	v_lshlrev_b32_e32 v16, 2, v44
	v_lshlrev_b32_e32 v43, 2, v40
	v_lshlrev_b32_e32 v45, 2, v41
	v_lshlrev_b32_e32 v46, 2, v42
	s_waitcnt vmcnt(0)
	v_mfma_f32_32x32x16_bf16 v[0:15], v[96:99], v[168:171], v[0:15]
	s_nop 11
	ds_write2st64_b32 v34, v0, v1 offset1:1
	ds_write2st64_b32 v34, v2, v3 offset0:2 offset1:3
	ds_write2st64_b32 v34, v4, v5 offset0:4 offset1:5
	ds_write2st64_b32 v34, v6, v7 offset0:6 offset1:7
	ds_write2st64_b32 v34, v8, v9 offset0:8 offset1:9
	ds_write2st64_b32 v34, v10, v11 offset0:10 offset1:11
	ds_write2st64_b32 v34, v12, v13 offset0:12 offset1:13
	ds_write2st64_b32 v34, v14, v15 offset0:14 offset1:15
	s_waitcnt lgkmcnt(0)
	s_barrier
; DI bfr f2bf(float a) { return (bfr)(pack2(a, 0.f) & 0xffffu); }
; DI int crow(int reg, int h) { return (reg & 3) + 8 * (reg >> 2) + 4 * h; }
; template <bool RS, class Epi, class RowF>
; DI void gemm_sample(const bfr* __restrict__ A, int lda, const bfr* __restrict__ Bt, int ldb, int K, int N, char* smem, Epi epi, RowF rowf) {
;     ...
; #pragma unroll
;     for (int q = 0; q < 16; ++q) red[(wid * 16 + q) * 64 + lane] = acc[q];
;     __syncthreads();
; #pragma unroll
;     for (int e = 0; e < 4; ++e) {
;       const int q = wid + e * 4;
;       const float v = red[q * 64 + lane] + red[(16 + q) * 64 + lane] + red[(32 + q) * 64 + lane] + red[(48 + q) * 64 + lane];
;       const int row = NPR + mu * 32 + crow(q, hl), col = nu * 32 + r;
;       float x = epi(row, col, v);
;       if (RS) {
;         float s2 = half32_sum_hi(x * x);
;         if (r == 31) rowf(row, s2);
;       }
;     }
; DI void phase_gemm_bf16out(const Params& p, const bfr* A, const bfr* Wt, bfr* C, int N, const float* ss, char* smem) {
;     ...
;                        float inv = rsqrtf(ss[row] * (1.0f / 1024.0f) + EPSF);
;                        C[(size_t)row * N + col] = f2bf(v * inv);
	global_load_dword v47, v16, s[8:9]
	global_load_dword v48, v43, s[8:9]
	global_load_dword v49, v45, s[8:9]
	global_load_dword v50, v46, s[8:9]
	v_or_b32_e32 v0, s0, v24
	v_ashrrev_i32_e32 v1, 31, v0
	v_lshl_add_u64 v[0:1], v[0:1], 1, s[2:3]
	v_lshlrev_b32_e32 v16, 11, v44
	v_lshl_add_u64 v[2:3], v[0:1], 0, v[16:17]
	v_lshlrev_b32_e32 v16, 11, v40
	v_lshl_add_u64 v[4:5], v[0:1], 0, v[16:17]
	v_lshlrev_b32_e32 v16, 11, v41
	v_lshl_add_u64 v[6:7], v[0:1], 0, v[16:17]
	v_lshlrev_b32_e32 v16, 11, v42
	ds_read2st64_b32 v[8:9], v26 offset1:16
	ds_read2st64_b32 v[10:11], v26 offset0:32 offset1:48
	ds_read2st64_b32 v[12:13], v28 offset1:16
	ds_read2st64_b32 v[14:15], v28 offset0:32 offset1:48
	ds_read2st64_b32 v[36:37], v30 offset1:16
	ds_read2st64_b32 v[38:39], v30 offset0:32 offset1:48
	ds_read2st64_b32 v[40:41], v32 offset1:16
	ds_read2st64_b32 v[42:43], v32 offset0:32 offset1:48
	s_waitcnt lgkmcnt(7)
	v_add_f32_e32 v8, v8, v9
	s_waitcnt lgkmcnt(5)
	v_add_f32_e32 v9, v12, v13
	s_waitcnt lgkmcnt(3)
	v_add_f32_e32 v12, v36, v37
	s_waitcnt lgkmcnt(1)
	v_add_f32_e32 v13, v40, v41
	v_add_f32_e32 v8, v8, v10
	v_add_f32_e32 v10, v12, v38
	s_waitcnt lgkmcnt(0)
	v_add_f32_e32 v12, v13, v42
	v_add_f32_e32 v9, v9, v14
	v_add_f32_e32 v8, v8, v11
	v_add_f32_e32 v11, v12, v43
	v_lshl_add_u64 v[0:1], v[0:1], 0, v[16:17]
	v_add_f32_e32 v9, v9, v15
	v_add_f32_e32 v10, v10, v39
	s_waitcnt vmcnt(3)
	v_fmamk_f32 v12, v47, 0x3a800000, v35
	s_waitcnt vmcnt(2)
	v_fmamk_f32 v13, v48, 0x3a800000, v35
	s_waitcnt vmcnt(1)
	v_fmamk_f32 v14, v49, 0x3a800000, v35
	s_waitcnt vmcnt(0)
	v_fmamk_f32 v15, v50, 0x3a800000, v35
	v_mul_f32_e32 v16, 0x4b800000, v12
	v_cmp_gt_f32_e64 s[6:7], s25, v12
	v_mul_f32_e32 v36, 0x4b800000, v13
	v_cmp_gt_f32_e32 vcc, s25, v13
	v_mul_f32_e32 v37, 0x4b800000, v14
	v_cmp_gt_f32_e64 s[0:1], s25, v14
	v_mul_f32_e32 v38, 0x4b800000, v15
	v_cmp_gt_f32_e64 s[4:5], s25, v15
	v_cndmask_b32_e64 v12, v12, v16, s[6:7]
	v_cndmask_b32_e32 v13, v13, v36, vcc
	v_cndmask_b32_e64 v14, v14, v37, s[0:1]
	v_cndmask_b32_e64 v15, v15, v38, s[4:5]
	v_rsq_f32_e32 v12, v12
	v_rsq_f32_e32 v13, v13
	v_rsq_f32_e32 v14, v14
	v_rsq_f32_e32 v15, v15
	v_mul_f32_e32 v16, 0x45800000, v12
	v_mul_f32_e32 v36, 0x45800000, v13
	v_mul_f32_e32 v37, 0x45800000, v14
	v_mul_f32_e32 v38, 0x45800000, v15
	v_cndmask_b32_e64 v12, v12, v16, s[6:7]
	v_cndmask_b32_e32 v13, v13, v36, vcc
	v_cndmask_b32_e64 v14, v14, v37, s[0:1]
	v_cndmask_b32_e64 v15, v15, v38, s[4:5]
	v_mul_f32_e32 v8, v8, v12
	v_mul_f32_e32 v9, v9, v13
	v_mul_f32_e32 v10, v10, v14
	v_mul_f32_e32 v11, v11, v15
	v_cvt_pk_bf16_f32 v8, v8, s0
	v_cvt_pk_bf16_f32 v9, v9, s0
	v_cvt_pk_bf16_f32 v10, v10, s0
	v_cvt_pk_bf16_f32 v11, v11, s0
	global_store_short v[2:3], v8, off
	global_store_short v[4:5], v9, off
	global_store_short v[6:7], v10, off
	global_store_short v[0:1], v11, off
	s_barrier
	s_cbranch_scc1 .LBB0_919

; #define MFMA32(a, b, c) __builtin_amdgcn_mfma_f32_32x32x16_bf16((a), (b), (c), 0, 0, 0)
; DI int crow(int reg, int h) { return (reg & 3) + 8 * (reg >> 2) + 4 * h; }
; template <bool RS, class Epi, class RowF>
; DI void gemm_sample(const bfr* __restrict__ A, int lda, const bfr* __restrict__ Bt, int ldb, int K, int N, char* smem, Epi epi, RowF rowf) {
;     ...
;     if (K == 1024) {
; #pragma unroll
;       for (int ks = 0; ks < 16; ++ks) {
;         bf16x8 af = *(const bf16x8*)(ap + ks * 16);
;         bf16x8 bf = *(const bf16x8*)(bp + (size_t)(ks >> 1) * ldb * 32 + (ks & 1) * 16);
;         acc = MFMA32(af, bf, acc);
;       }
;     } else {
;       for (int ks = 0; ks < (kq >> 4); ++ks) {
;         bf16x8 af = *(const bf16x8*)(ap + ks * 16);
;         bf16x8 bf = *(const bf16x8*)(bp + (size_t)(ks >> 1) * ldb * 32 + (ks & 1) * 16);
;         acc = MFMA32(af, bf, acc);
;       }
;     }
; #pragma unroll
;     for (int q = 0; q < 16; ++q) red[(wid * 16 + q) * 64 + lane] = acc[q];
;     __syncthreads();
; #pragma unroll
;     for (int e = 0; e < 4; ++e) {
;       const int q = wid + e * 4;
;       const float v = red[q * 64 + lane] + red[(16 + q) * 64 + lane] + red[(32 + q) * 64 + lane] + red[(48 + q) * 64 + lane];
;       const int row = NPR + mu * 32 + crow(q, hl), col = nu * 32 + r;
.LBB0_1175:
	s_and_b32 s1, s16, 0x60
	s_and_b32 s0, s14, 0xffffffe0
	s_or_b32 s4, s1, 0x4000
	s_ashr_i32 s1, s0, 31
	v_or_b32_e32 v2, s4, v24
	v_lshl_add_u64 v[0:1], s[0:1], 0, v[20:21]
	v_lshlrev_b32_e32 v16, 11, v2
	v_lshlrev_b64 v[0:1], 6, v[0:1]
	v_lshl_add_u64 v[8:9], v[18:19], 0, v[16:17]
	v_lshl_add_u64 v[10:11], v[22:23], 0, v[0:1]
	global_load_dwordx4 v[0:3], v[8:9], off
	global_load_dwordx4 v[4:7], v[10:11], off
	global_load_dwordx4 v[36:39], v[8:9], off offset:32
	global_load_dwordx4 v[40:43], v[10:11], off offset:32
	v_add_co_u32_e32 v104, vcc, s18, v10
	global_load_dwordx4 v[44:47], v[8:9], off offset:64
	global_load_dwordx4 v[48:51], v[8:9], off offset:96
	v_addc_co_u32_e32 v105, vcc, 0, v11, vcc
	v_add_co_u32_e32 v106, vcc, s19, v10
	global_load_dwordx4 v[52:55], v[8:9], off offset:128
	global_load_dwordx4 v[56:59], v[8:9], off offset:160
	v_addc_co_u32_e32 v107, vcc, 0, v11, vcc
	v_add_co_u32_e32 v108, vcc, s20, v10
	global_load_dwordx4 v[60:63], v[8:9], off offset:192
	global_load_dwordx4 v[64:67], v[8:9], off offset:224
	v_addc_co_u32_e32 v109, vcc, 0, v11, vcc
	v_add_co_u32_e32 v110, vcc, s21, v10
	global_load_dwordx4 v[68:71], v[8:9], off offset:256
	global_load_dwordx4 v[72:75], v[8:9], off offset:288
	v_addc_co_u32_e32 v111, vcc, 0, v11, vcc
	v_add_co_u32_e32 v112, vcc, s22, v10
	global_load_dwordx4 v[76:79], v[8:9], off offset:320
	global_load_dwordx4 v[80:83], v[8:9], off offset:352
	v_addc_co_u32_e32 v113, vcc, 0, v11, vcc
	v_add_co_u32_e32 v114, vcc, s23, v10
	global_load_dwordx4 v[84:87], v[8:9], off offset:384
	global_load_dwordx4 v[88:91], v[8:9], off offset:416
	v_addc_co_u32_e32 v115, vcc, 0, v11, vcc
	v_add_co_u32_e32 v116, vcc, s24, v10
	global_load_dwordx4 v[92:95], v[8:9], off offset:448
	global_load_dwordx4 v[96:99], v[8:9], off offset:480
	v_addc_co_u32_e32 v117, vcc, 0, v11, vcc
	global_load_dwordx4 v[100:103], v[104:105], off
	v_or_b32_e32 v16, s4, v25
	s_add_i32 s26, s26, s34
	s_add_i32 s14, s14, s15
	s_add_i32 s16, s16, s17
	s_cmpk_lt_i32 s26, 0x100
	global_load_dwordx4 v[120:123], v[104:105], off offset:32
	global_load_dwordx4 v[124:127], v[106:107], off
	global_load_dwordx4 v[128:131], v[106:107], off offset:32
	global_load_dwordx4 v[132:135], v[108:109], off
	global_load_dwordx4 v[136:139], v[108:109], off offset:32
	global_load_dwordx4 v[140:143], v[110:111], off
	global_load_dwordx4 v[144:147], v[110:111], off offset:32
	global_load_dwordx4 v[148:151], v[112:113], off
	global_load_dwordx4 v[152:155], v[112:113], off offset:32
	global_load_dwordx4 v[156:159], v[114:115], off
	global_load_dwordx4 v[160:163], v[114:115], off offset:32
	global_load_dwordx4 v[164:167], v[116:117], off
	global_load_dwordx4 v[168:171], v[116:117], off offset:32
	s_waitcnt vmcnt(30)
	v_mfma_f32_32x32x16_bf16 v[0:15], v[0:3], v[4:7], 0
	s_waitcnt vmcnt(28)
	v_mfma_f32_32x32x16_bf16 v[0:15], v[36:39], v[40:43], v[0:15]
	s_waitcnt vmcnt(13)
	v_mfma_f32_32x32x16_bf16 v[0:15], v[44:47], v[100:103], v[0:15]
	v_or_b32_e32 v44, v27, v16
	s_waitcnt vmcnt(12)
	v_mfma_f32_32x32x16_bf16 v[0:15], v[48:51], v[120:123], v[0:15]
	s_waitcnt vmcnt(11)
	v_mfma_f32_32x32x16_bf16 v[0:15], v[52:55], v[124:127], v[0:15]
	s_waitcnt vmcnt(10)
	v_mfma_f32_32x32x16_bf16 v[0:15], v[56:59], v[128:131], v[0:15]
	s_waitcnt vmcnt(9)
	v_mfma_f32_32x32x16_bf16 v[0:15], v[60:63], v[132:135], v[0:15]
	s_waitcnt vmcnt(8)
	v_mfma_f32_32x32x16_bf16 v[0:15], v[64:67], v[136:139], v[0:15]
	s_waitcnt vmcnt(7)
	v_mfma_f32_32x32x16_bf16 v[0:15], v[68:71], v[140:143], v[0:15]
	s_waitcnt vmcnt(6)
	v_mfma_f32_32x32x16_bf16 v[0:15], v[72:75], v[144:147], v[0:15]
	s_waitcnt vmcnt(5)
	v_mfma_f32_32x32x16_bf16 v[0:15], v[76:79], v[148:151], v[0:15]
	s_waitcnt vmcnt(4)
	v_mfma_f32_32x32x16_bf16 v[0:15], v[80:83], v[152:155], v[0:15]
	s_waitcnt vmcnt(3)
	v_mfma_f32_32x32x16_bf16 v[0:15], v[84:87], v[156:159], v[0:15]
	s_waitcnt vmcnt(2)
	v_mfma_f32_32x32x16_bf16 v[0:15], v[88:91], v[160:163], v[0:15]
	s_waitcnt vmcnt(1)
	v_mfma_f32_32x32x16_bf16 v[0:15], v[92:95], v[164:167], v[0:15]
	v_add_u32_e32 v40, v16, v29
	v_add_u32_e32 v41, v16, v31
	v_add_u32_e32 v42, v16, v33
	v_lshlrev_b32_e32 v16, 2, v44
	v_lshlrev_b32_e32 v43, 2, v40
	v_lshlrev_b32_e32 v45, 2, v41
	v_lshlrev_b32_e32 v46, 2, v42
	s_waitcnt vmcnt(0)
	v_mfma_f32_32x32x16_bf16 v[0:15], v[96:99], v[168:171], v[0:15]
	s_nop 11
	ds_write2st64_b32 v34, v0, v1 offset1:1
	ds_write2st64_b32 v34, v2, v3 offset0:2 offset1:3
	ds_write2st64_b32 v34, v4, v5 offset0:4 offset1:5
	ds_write2st64_b32 v34, v6, v7 offset0:6 offset1:7
	ds_write2st64_b32 v34, v8, v9 offset0:8 offset1:9
	ds_write2st64_b32 v34, v10, v11 offset0:10 offset1:11
	ds_write2st64_b32 v34, v12, v13 offset0:12 offset1:13
	ds_write2st64_b32 v34, v14, v15 offset0:14 offset1:15
	s_waitcnt lgkmcnt(0)
	s_barrier
; DI bfr f2bf(float a) { return (bfr)(pack2(a, 0.f) & 0xffffu); }
; DI int crow(int reg, int h) { return (reg & 3) + 8 * (reg >> 2) + 4 * h; }
; template <bool RS, class Epi, class RowF>
; DI void gemm_sample(const bfr* __restrict__ A, int lda, const bfr* __restrict__ Bt, int ldb, int K, int N, char* smem, Epi epi, RowF rowf) {
;     ...
; #pragma unroll
;     for (int q = 0; q < 16; ++q) red[(wid * 16 + q) * 64 + lane] = acc[q];
;     __syncthreads();
; #pragma unroll
;     for (int e = 0; e < 4; ++e) {
;       const int q = wid + e * 4;
;       const float v = red[q * 64 + lane] + red[(16 + q) * 64 + lane] + red[(32 + q) * 64 + lane] + red[(48 + q) * 64 + lane];
;       const int row = NPR + mu * 32 + crow(q, hl), col = nu * 32 + r;
;       float x = epi(row, col, v);
;       if (RS) {
;         float s2 = half32_sum_hi(x * x);
;         if (r == 31) rowf(row, s2);
;       }
;     }
; DI void phase_gemm_bf16out(const Params& p, const bfr* A, const bfr* Wt, bfr* C, int N, const float* ss, char* smem) {
;     ...
;                        float inv = rsqrtf(ss[row] * (1.0f / 1024.0f) + EPSF);
;                        C[(size_t)row * N + col] = f2bf(v * inv);
	global_load_dword v47, v16, s[8:9]
	global_load_dword v48, v43, s[8:9]
	global_load_dword v49, v45, s[8:9]
	global_load_dword v50, v46, s[8:9]
	v_or_b32_e32 v0, s0, v24
	v_ashrrev_i32_e32 v1, 31, v0
	v_lshl_add_u64 v[0:1], v[0:1], 1, s[2:3]
	v_lshlrev_b32_e32 v16, 12, v44
	v_lshl_add_u64 v[2:3], v[0:1], 0, v[16:17]
	v_lshlrev_b32_e32 v16, 12, v40
	v_lshl_add_u64 v[4:5], v[0:1], 0, v[16:17]
	v_lshlrev_b32_e32 v16, 12, v41
	v_lshl_add_u64 v[6:7], v[0:1], 0, v[16:17]
	v_lshlrev_b32_e32 v16, 12, v42
	ds_read2st64_b32 v[8:9], v26 offset1:16
	ds_read2st64_b32 v[10:11], v26 offset0:32 offset1:48
	ds_read2st64_b32 v[12:13], v28 offset1:16
	ds_read2st64_b32 v[14:15], v28 offset0:32 offset1:48
	ds_read2st64_b32 v[36:37], v30 offset1:16
	ds_read2st64_b32 v[38:39], v30 offset0:32 offset1:48
	ds_read2st64_b32 v[40:41], v32 offset1:16
	ds_read2st64_b32 v[42:43], v32 offset0:32 offset1:48
	s_waitcnt lgkmcnt(7)
	v_add_f32_e32 v8, v8, v9
	s_waitcnt lgkmcnt(5)
	v_add_f32_e32 v9, v12, v13
	s_waitcnt lgkmcnt(3)
	v_add_f32_e32 v12, v36, v37
	s_waitcnt lgkmcnt(1)
	v_add_f32_e32 v13, v40, v41
	v_add_f32_e32 v8, v8, v10
	v_add_f32_e32 v10, v12, v38
	s_waitcnt lgkmcnt(0)
	v_add_f32_e32 v12, v13, v42
	v_add_f32_e32 v9, v9, v14
	v_add_f32_e32 v8, v8, v11
	v_add_f32_e32 v11, v12, v43
	v_lshl_add_u64 v[0:1], v[0:1], 0, v[16:17]
	v_add_f32_e32 v9, v9, v15
	v_add_f32_e32 v10, v10, v39
	s_waitcnt vmcnt(3)
	v_fmamk_f32 v12, v47, 0x3a800000, v35
	s_waitcnt vmcnt(2)
	v_fmamk_f32 v13, v48, 0x3a800000, v35
	s_waitcnt vmcnt(1)
	v_fmamk_f32 v14, v49, 0x3a800000, v35
	s_waitcnt vmcnt(0)
	v_fmamk_f32 v15, v50, 0x3a800000, v35
	v_mul_f32_e32 v16, 0x4b800000, v12
	v_cmp_gt_f32_e64 s[6:7], s25, v12
	v_mul_f32_e32 v36, 0x4b800000, v13
	v_cmp_gt_f32_e32 vcc, s25, v13
	v_mul_f32_e32 v37, 0x4b800000, v14
	v_cmp_gt_f32_e64 s[0:1], s25, v14
	v_mul_f32_e32 v38, 0x4b800000, v15
	v_cmp_gt_f32_e64 s[4:5], s25, v15
	v_cndmask_b32_e64 v12, v12, v16, s[6:7]
	v_cndmask_b32_e32 v13, v13, v36, vcc
	v_cndmask_b32_e64 v14, v14, v37, s[0:1]
	v_cndmask_b32_e64 v15, v15, v38, s[4:5]
	v_rsq_f32_e32 v12, v12
	v_rsq_f32_e32 v13, v13
	v_rsq_f32_e32 v14, v14
	v_rsq_f32_e32 v15, v15
	v_mul_f32_e32 v16, 0x45800000, v12
	v_mul_f32_e32 v36, 0x45800000, v13
	v_mul_f32_e32 v37, 0x45800000, v14
	v_mul_f32_e32 v38, 0x45800000, v15
	v_cndmask_b32_e64 v12, v12, v16, s[6:7]
	v_cndmask_b32_e32 v13, v13, v36, vcc
	v_cndmask_b32_e64 v14, v14, v37, s[0:1]
	v_cndmask_b32_e64 v15, v15, v38, s[4:5]
	v_mul_f32_e32 v8, v8, v12
	v_mul_f32_e32 v9, v9, v13
	v_mul_f32_e32 v10, v10, v14
	v_mul_f32_e32 v11, v11, v15
	v_cvt_pk_bf16_f32 v8, v8, s0
	v_cvt_pk_bf16_f32 v9, v9, s0
	v_cvt_pk_bf16_f32 v10, v10, s0
	v_cvt_pk_bf16_f32 v11, v11, s0
	global_store_short v[2:3], v8, off
	global_store_short v[4:5], v9, off
	global_store_short v[6:7], v10, off
	global_store_short v[0:1], v11, off
	s_barrier
	s_cbranch_scc1 .LBB0_1175

; #define MFMA32(a, b, c) __builtin_amdgcn_mfma_f32_32x32x16_bf16((a), (b), (c), 0, 0, 0)
; DI int crow(int reg, int h) { return (reg & 3) + 8 * (reg >> 2) + 4 * h; }
; template <bool RS, class Epi, class RowF>
; DI void gemm_sample(const bfr* __restrict__ A, int lda, const bfr* __restrict__ Bt, int ldb, int K, int N, char* smem, Epi epi, RowF rowf) {
;     ...
;     if (K == 1024) {
; #pragma unroll
;       for (int ks = 0; ks < 16; ++ks) {
;         bf16x8 af = *(const bf16x8*)(ap + ks * 16);
;         bf16x8 bf = *(const bf16x8*)(bp + (size_t)(ks >> 1) * ldb * 32 + (ks & 1) * 16);
;         acc = MFMA32(af, bf, acc);
;       }
;     } else {
;       for (int ks = 0; ks < (kq >> 4); ++ks) {
;         bf16x8 af = *(const bf16x8*)(ap + ks * 16);
;         bf16x8 bf = *(const bf16x8*)(bp + (size_t)(ks >> 1) * ldb * 32 + (ks & 1) * 16);
;         acc = MFMA32(af, bf, acc);
;       }
;     }
; #pragma unroll
;     for (int q = 0; q < 16; ++q) red[(wid * 16 + q) * 64 + lane] = acc[q];
;     __syncthreads();
; #pragma unroll
;     for (int e = 0; e < 4; ++e) {
;       const int q = wid + e * 4;
;       const float v = red[q * 64 + lane] + red[(16 + q) * 64 + lane] + red[(32 + q) * 64 + lane] + red[(48 + q) * 64 + lane];
;       const int row = NPR + mu * 32 + crow(q, hl), col = nu * 32 + r;
.LBB0_1542:
	s_and_b32 s1, s18, 0x60
	s_and_b32 s0, s16, 0xffffffe0
	s_or_b32 s4, s1, 0x4000
	s_ashr_i32 s1, s0, 31
	v_or_b32_e32 v2, s4, v24
	v_lshl_add_u64 v[0:1], s[0:1], 0, v[20:21]
	v_lshlrev_b32_e32 v16, 11, v2
	v_lshlrev_b64 v[0:1], 6, v[0:1]
	v_lshl_add_u64 v[8:9], v[18:19], 0, v[16:17]
	v_lshl_add_u64 v[10:11], v[22:23], 0, v[0:1]
	global_load_dwordx4 v[0:3], v[8:9], off
	global_load_dwordx4 v[4:7], v[10:11], off
	global_load_dwordx4 v[36:39], v[8:9], off offset:32
	global_load_dwordx4 v[40:43], v[10:11], off offset:32
	v_add_co_u32_e32 v104, vcc, s20, v10
	global_load_dwordx4 v[44:47], v[8:9], off offset:64
	global_load_dwordx4 v[48:51], v[8:9], off offset:96
	v_addc_co_u32_e32 v105, vcc, 0, v11, vcc
	v_add_co_u32_e32 v106, vcc, s21, v10
	global_load_dwordx4 v[52:55], v[8:9], off offset:128
	global_load_dwordx4 v[56:59], v[8:9], off offset:160
	v_addc_co_u32_e32 v107, vcc, 0, v11, vcc
	v_add_co_u32_e32 v108, vcc, s22, v10
	global_load_dwordx4 v[60:63], v[8:9], off offset:192
	global_load_dwordx4 v[64:67], v[8:9], off offset:224
	v_addc_co_u32_e32 v109, vcc, 0, v11, vcc
	v_add_co_u32_e32 v110, vcc, s23, v10
	global_load_dwordx4 v[68:71], v[8:9], off offset:256
	global_load_dwordx4 v[72:75], v[8:9], off offset:288
	v_addc_co_u32_e32 v111, vcc, 0, v11, vcc
	v_add_co_u32_e32 v112, vcc, s24, v10
	global_load_dwordx4 v[76:79], v[8:9], off offset:320
	global_load_dwordx4 v[80:83], v[8:9], off offset:352
	v_addc_co_u32_e32 v113, vcc, 0, v11, vcc
	v_add_co_u32_e32 v114, vcc, s25, v10
	global_load_dwordx4 v[84:87], v[8:9], off offset:384
	global_load_dwordx4 v[88:91], v[8:9], off offset:416
	v_addc_co_u32_e32 v115, vcc, 0, v11, vcc
	v_add_co_u32_e32 v116, vcc, s26, v10
	global_load_dwordx4 v[92:95], v[8:9], off offset:448
	global_load_dwordx4 v[96:99], v[8:9], off offset:480
	v_addc_co_u32_e32 v117, vcc, 0, v11, vcc
	global_load_dwordx4 v[100:103], v[104:105], off
	v_or_b32_e32 v16, s4, v25
	s_add_i32 s28, s28, s34
	s_add_i32 s16, s16, s17
	s_add_i32 s18, s18, s19
	s_cmpk_lt_i32 s28, 0x80
	global_load_dwordx4 v[120:123], v[104:105], off offset:32
	global_load_dwordx4 v[124:127], v[106:107], off
	global_load_dwordx4 v[128:131], v[106:107], off offset:32
	global_load_dwordx4 v[132:135], v[108:109], off
	global_load_dwordx4 v[136:139], v[108:109], off offset:32
	global_load_dwordx4 v[140:143], v[110:111], off
	global_load_dwordx4 v[144:147], v[110:111], off offset:32
	global_load_dwordx4 v[148:151], v[112:113], off
	global_load_dwordx4 v[152:155], v[112:113], off offset:32
	global_load_dwordx4 v[156:159], v[114:115], off
	global_load_dwordx4 v[160:163], v[114:115], off offset:32
	global_load_dwordx4 v[164:167], v[116:117], off
	global_load_dwordx4 v[168:171], v[116:117], off offset:32
	s_waitcnt vmcnt(30)
	v_mfma_f32_32x32x16_bf16 v[0:15], v[0:3], v[4:7], 0
	s_waitcnt vmcnt(28)
	v_mfma_f32_32x32x16_bf16 v[0:15], v[36:39], v[40:43], v[0:15]
	s_waitcnt vmcnt(13)
	v_mfma_f32_32x32x16_bf16 v[0:15], v[44:47], v[100:103], v[0:15]
	v_or_b32_e32 v44, v27, v16
	s_waitcnt vmcnt(12)
	v_mfma_f32_32x32x16_bf16 v[0:15], v[48:51], v[120:123], v[0:15]
	s_waitcnt vmcnt(11)
	v_mfma_f32_32x32x16_bf16 v[0:15], v[52:55], v[124:127], v[0:15]
	s_waitcnt vmcnt(10)
	v_mfma_f32_32x32x16_bf16 v[0:15], v[56:59], v[128:131], v[0:15]
	s_waitcnt vmcnt(9)
	v_mfma_f32_32x32x16_bf16 v[0:15], v[60:63], v[132:135], v[0:15]
	s_waitcnt vmcnt(8)
	v_mfma_f32_32x32x16_bf16 v[0:15], v[64:67], v[136:139], v[0:15]
	s_waitcnt vmcnt(7)
	v_mfma_f32_32x32x16_bf16 v[0:15], v[68:71], v[140:143], v[0:15]
	s_waitcnt vmcnt(6)
	v_mfma_f32_32x32x16_bf16 v[0:15], v[72:75], v[144:147], v[0:15]
	s_waitcnt vmcnt(5)
	v_mfma_f32_32x32x16_bf16 v[0:15], v[76:79], v[148:151], v[0:15]
	s_waitcnt vmcnt(4)
	v_mfma_f32_32x32x16_bf16 v[0:15], v[80:83], v[152:155], v[0:15]
	s_waitcnt vmcnt(3)
	v_mfma_f32_32x32x16_bf16 v[0:15], v[84:87], v[156:159], v[0:15]
	s_waitcnt vmcnt(2)
	v_mfma_f32_32x32x16_bf16 v[0:15], v[88:91], v[160:163], v[0:15]
	s_waitcnt vmcnt(1)
	v_mfma_f32_32x32x16_bf16 v[0:15], v[92:95], v[164:167], v[0:15]
	v_add_u32_e32 v40, v16, v29
	v_add_u32_e32 v41, v16, v31
	v_add_u32_e32 v42, v16, v33
	v_lshlrev_b32_e32 v16, 2, v44
	v_lshlrev_b32_e32 v43, 2, v40
	v_lshlrev_b32_e32 v45, 2, v41
	v_lshlrev_b32_e32 v46, 2, v42
	s_waitcnt vmcnt(0)
	v_mfma_f32_32x32x16_bf16 v[0:15], v[96:99], v[168:171], v[0:15]
	s_nop 11
	ds_write2st64_b32 v34, v0, v1 offset1:1
	ds_write2st64_b32 v34, v2, v3 offset0:2 offset1:3
	ds_write2st64_b32 v34, v4, v5 offset0:4 offset1:5
	ds_write2st64_b32 v34, v6, v7 offset0:6 offset1:7
	ds_write2st64_b32 v34, v8, v9 offset0:8 offset1:9
	ds_write2st64_b32 v34, v10, v11 offset0:10 offset1:11
	ds_write2st64_b32 v34, v12, v13 offset0:12 offset1:13
	ds_write2st64_b32 v34, v14, v15 offset0:14 offset1:15
	s_waitcnt lgkmcnt(0)
	s_barrier
; DI bfr f2bf(float a) { return (bfr)(pack2(a, 0.f) & 0xffffu); }
; DI int crow(int reg, int h) { return (reg & 3) + 8 * (reg >> 2) + 4 * h; }
; template <bool RS, class Epi, class RowF>
; DI void gemm_sample(const bfr* __restrict__ A, int lda, const bfr* __restrict__ Bt, int ldb, int K, int N, char* smem, Epi epi, RowF rowf) {
;     ...
; #pragma unroll
;     for (int q = 0; q < 16; ++q) red[(wid * 16 + q) * 64 + lane] = acc[q];
;     __syncthreads();
; #pragma unroll
;     for (int e = 0; e < 4; ++e) {
;       const int q = wid + e * 4;
;       const float v = red[q * 64 + lane] + red[(16 + q) * 64 + lane] + red[(32 + q) * 64 + lane] + red[(48 + q) * 64 + lane];
;       const int row = NPR + mu * 32 + crow(q, hl), col = nu * 32 + r;
;       float x = epi(row, col, v);
;       if (RS) {
;         float s2 = half32_sum_hi(x * x);
;         if (r == 31) rowf(row, s2);
;       }
;     }
; DI void phase_gemm_bf16out(const Params& p, const bfr* A, const bfr* Wt, bfr* C, int N, const float* ss, char* smem) {
;     ...
;                        float inv = rsqrtf(ss[row] * (1.0f / 1024.0f) + EPSF);
;                        C[(size_t)row * N + col] = f2bf(v * inv);
	global_load_dword v47, v16, s[8:9]
	global_load_dword v48, v43, s[8:9]
	global_load_dword v49, v45, s[8:9]
	global_load_dword v50, v46, s[8:9]
	v_or_b32_e32 v0, s0, v24
	v_ashrrev_i32_e32 v1, 31, v0
	v_lshl_add_u64 v[0:1], v[0:1], 1, s[12:13]
	v_lshlrev_b32_e32 v16, 11, v44
	v_lshl_add_u64 v[2:3], v[0:1], 0, v[16:17]
	v_lshlrev_b32_e32 v16, 11, v40
	v_lshl_add_u64 v[4:5], v[0:1], 0, v[16:17]
	v_lshlrev_b32_e32 v16, 11, v41
	v_lshl_add_u64 v[6:7], v[0:1], 0, v[16:17]
	v_lshlrev_b32_e32 v16, 11, v42
	ds_read2st64_b32 v[8:9], v26 offset1:16
	ds_read2st64_b32 v[10:11], v26 offset0:32 offset1:48
	ds_read2st64_b32 v[12:13], v28 offset1:16
	ds_read2st64_b32 v[14:15], v28 offset0:32 offset1:48
	ds_read2st64_b32 v[36:37], v30 offset1:16
	ds_read2st64_b32 v[38:39], v30 offset0:32 offset1:48
	ds_read2st64_b32 v[40:41], v32 offset1:16
	ds_read2st64_b32 v[42:43], v32 offset0:32 offset1:48
	s_waitcnt lgkmcnt(7)
	v_add_f32_e32 v8, v8, v9
	s_waitcnt lgkmcnt(5)
	v_add_f32_e32 v9, v12, v13
	s_waitcnt lgkmcnt(3)
	v_add_f32_e32 v12, v36, v37
	s_waitcnt lgkmcnt(1)
	v_add_f32_e32 v13, v40, v41
	v_add_f32_e32 v8, v8, v10
	v_add_f32_e32 v10, v12, v38
	s_waitcnt lgkmcnt(0)
	v_add_f32_e32 v12, v13, v42
	v_add_f32_e32 v9, v9, v14
	v_add_f32_e32 v8, v8, v11
	v_add_f32_e32 v11, v12, v43
	v_lshl_add_u64 v[0:1], v[0:1], 0, v[16:17]
	v_add_f32_e32 v9, v9, v15
	v_add_f32_e32 v10, v10, v39
	s_waitcnt vmcnt(3)
	v_fmamk_f32 v12, v47, 0x3a800000, v35
	s_waitcnt vmcnt(2)
	v_fmamk_f32 v13, v48, 0x3a800000, v35
	s_waitcnt vmcnt(1)
	v_fmamk_f32 v14, v49, 0x3a800000, v35
	s_waitcnt vmcnt(0)
	v_fmamk_f32 v15, v50, 0x3a800000, v35
	v_mul_f32_e32 v16, 0x4b800000, v12
	v_cmp_gt_f32_e64 s[6:7], s27, v12
	v_mul_f32_e32 v36, 0x4b800000, v13
	v_cmp_gt_f32_e32 vcc, s27, v13
	v_mul_f32_e32 v37, 0x4b800000, v14
	v_cmp_gt_f32_e64 s[0:1], s27, v14
	v_mul_f32_e32 v38, 0x4b800000, v15
	v_cmp_gt_f32_e64 s[4:5], s27, v15
	v_cndmask_b32_e64 v12, v12, v16, s[6:7]
	v_cndmask_b32_e32 v13, v13, v36, vcc
	v_cndmask_b32_e64 v14, v14, v37, s[0:1]
	v_cndmask_b32_e64 v15, v15, v38, s[4:5]
	v_rsq_f32_e32 v12, v12
	v_rsq_f32_e32 v13, v13
	v_rsq_f32_e32 v14, v14
	v_rsq_f32_e32 v15, v15
	v_mul_f32_e32 v16, 0x45800000, v12
	v_mul_f32_e32 v36, 0x45800000, v13
	v_mul_f32_e32 v37, 0x45800000, v14
	v_mul_f32_e32 v38, 0x45800000, v15
	v_cndmask_b32_e64 v12, v12, v16, s[6:7]
	v_cndmask_b32_e32 v13, v13, v36, vcc
	v_cndmask_b32_e64 v14, v14, v37, s[0:1]
	v_cndmask_b32_e64 v15, v15, v38, s[4:5]
	v_mul_f32_e32 v8, v8, v12
	v_mul_f32_e32 v9, v9, v13
	v_mul_f32_e32 v10, v10, v14
	v_mul_f32_e32 v11, v11, v15
	v_cvt_pk_bf16_f32 v8, v8, s0
	v_cvt_pk_bf16_f32 v9, v9, s0
	v_cvt_pk_bf16_f32 v10, v10, s0
	v_cvt_pk_bf16_f32 v11, v11, s0
	global_store_short v[2:3], v8, off
	global_store_short v[4:5], v9, off
	global_store_short v[6:7], v10, off
	global_store_short v[0:1], v11, off
	s_barrier
	s_cbranch_scc1 .LBB0_1542
